# INA start stagger step doubled (s_sleep 32)
# baseline (speedup 1.0000x reference)
.Lstag_795_loop:
	s_sleep 32
	s_sub_i32 s98, s98, 1
	s_cmp_lg_u32 s98, 0
	s_cbranch_scc1 .Lstag_795_loop
